# v34 + half-tile start stagger for blocks >= 256 in first ffn_in phase (de-synchronise the two co-resident blocks' epilogues)
# speedup vs baseline: 1.0306x; 1.0041x over previous
; template <bool RES, class Epi>
; DEV void gemm_tile_x(const bf16_t* A0, int lda0, const bf16_t* A1, int lda1, int ksplit,
;                      const bf16_t* Bt, int ldb, int K, char* smem, const float* resb, Epi epi) {
;     ...
;   const int tid = threadIdx.x, lane = tid & 63, wv = tid >> 6;
;   const int wm = wv >> 1, wn = wv & 1;
;   f32x16 acc[4][2];
; #pragma unroll
;   for (int i = 0; i < 4; ++i)
; #pragma unroll
;     for (int j = 0; j < 2; ++j)
; #pragma unroll
;       for (int r = 0; r < 16; ++r) acc[i][j][r] = 0.f;
;   GRegs g, g1;
;   const int nk = K >> 5;
;   const int woff = (tid >> 2) * 32 + (((tid & 3) ^ ((tid >> 4) & 3)) << 3);
;   const int swz = (lane >> 2) & 3, hh = lane >> 5;
;   const int raoff = (wm * 128 + (lane & 31)) * 32;
;   const int rboff = GSA + (wn * 64 + (lane & 31)) * 32;
; __device__ __forceinline__ void xcd_barrier_complete(unsigned* bar, unsigned x, unsigned& nloc, unsigned& nx) {
;     const unsigned G = gridDim.x * gridDim.y * gridDim.z;
;     unsigned sum, cnt, mine, sp = 0u;
;     for (;;) {
;         sum = 0u; cnt = 0u; mine = 0u;
; #pragma unroll
;         for (unsigned j = 0; j < 16; ++j) { const unsigned c = xb_ld(&bar[XB_XCNT(j)]); sum += c; cnt += (c > 0u) ? 1u : 0u; mine = (j == x) ? c : mine; }
;         if (sum == G) break;
;         __builtin_amdgcn_s_sleep(1);
;         if ((++sp & 255u) == 0u) { if (xb_ld(&bar[XB_TMO])) break; if (sp > XB_SPIN_CAP) { atomicAdd(&bar[XB_TMO], 1u); break; } }
;     }
;     nloc = mine > 0u ? mine : 1u; nx = cnt > 0u ? cnt : 1u;
; }
; __device__ __forceinline__ void xcd_barrier(const XcdBarrier& b) {
;     asm volatile("s_waitcnt vmcnt(0)" ::: "memory");
;     __syncthreads();
;     if (threadIdx.x == 0) {
;         unsigned* bar = b.bar;
;         __builtin_amdgcn_s_waitcnt(0);
;         unsigned nloc = b.st[0], nx = b.st[1];
;         if (nloc == 0u) { xcd_barrier_complete(bar, b.x, nloc, nx); b.st[0] = nloc; b.st[1] = nx; }
;         const unsigned old = xb_add(&bar[XB_XSUB(b.x)], 1u);
;         const unsigned gen = old / nloc;
;         if (old + 1u == (gen + 1u) * nloc) {
;             __builtin_amdgcn_fence(__ATOMIC_RELEASE, "agent");
;             asm volatile("s_waitcnt vmcnt(0)" ::: "memory");
;             const unsigned og = xb_add(&bar[XB_TOP], 1u);
;             const unsigned tg = og / nx;
;             if (og + 1u == (tg + 1u) * nx) xb_add(&bar[XB_TOPGEN], 1u);
.LBB0_166:
	s_waitcnt lgkmcnt(0)
	s_cmp_gt_i32 s24, 1
	s_cselect_b64 s[0:1], -1, 0
	s_cmp_lt_i32 s25, 2
	s_cselect_b64 s[2:3], -1, 0
	s_or_b64 s[0:1], s[0:1], s[2:3]
	v_bfe_u32 v181, v176, 2, 2
	v_bfe_u32 v222, v176, 5, 1
	s_and_b64 vcc, exec, s[0:1]
	v_lshrrev_b32_e32 v221, 4, v176
	v_lshrrev_b32_e32 v220, 2, v176
	v_bitop3_b32 v218, v222, v181, 2 bitop3:0x36
	v_lshlrev_b32_e32 v219, 6, v176
	v_lshrrev_b32_e32 v223, 1, v176
	v_and_b32_e32 v177, 3, v176
	s_cbranch_vccnz .LBB0_249
	s_load_dwordx2 s[0:1], s[38:39], 0x170
	s_bfe_u32 s33, s26, 0x10001
	s_add_u32 s84, s54, 0x7b00000
	s_addc_u32 s85, s55, 0
	v_xor_b32_e32 v1, v221, v176
	s_waitcnt lgkmcnt(0)
	s_lshr_b32 s86, s0, 3
	v_readlane_b32 s0, v250, 0
	s_lshr_b32 s87, s0, 3
	s_cmp_lt_u32 s0, 0x100
	s_cbranch_scc1 .LstagA0
	s_sleep 127
	s_sleep 127
	s_sleep 127
	s_sleep 127
	s_sleep 127
	s_sleep 127
.LstagA0:
	v_readlane_b32 s1, v250, 1
	s_cmpk_lt_u32 s0, 0x2100
	s_mov_b32 s4, s0
	s_cselect_b64 s[0:1], -1, 0
	s_cmp_gt_u32 s25, 2
	s_cselect_b64 s[2:3], -1, 0
	s_and_b32 s88, s4, 7
	s_cmp_gt_i32 s24, -1
	s_cselect_b64 s[4:5], -1, 0
	s_add_u32 s89, s54, 0x1cfc0000
	s_addc_u32 s90, s55, 0
	s_add_u32 s8, s54, 0x1cfc0200
	s_addc_u32 s9, s55, 0
	s_add_u32 s10, s54, 0x1cfc0400
	s_addc_u32 s11, s55, 0
	s_add_u32 s12, s54, 0x1cfc0500
	s_addc_u32 s13, s55, 0
	s_add_u32 s14, s54, 0x1cfc0600
	s_addc_u32 s15, s55, 0
	s_add_u32 s16, s54, 0x1cfc0700
	s_addc_u32 s17, s55, 0
	s_add_u32 s18, s54, 0x1cfc0800
	s_addc_u32 s19, s55, 0
	s_add_u32 s20, s54, 0x1cfc0900
	s_addc_u32 s21, s55, 0
	s_add_u32 s22, s54, 0x1cfc0a00
	s_addc_u32 s23, s55, 0
	s_add_u32 s24, s54, 0x1cfc0b00
	s_addc_u32 s25, s55, 0
	s_add_u32 s26, s54, 0x1cfc0c00
	s_addc_u32 s27, s55, 0
	s_add_u32 s28, s54, 0x1cfc0d00
	s_addc_u32 s29, s55, 0
	s_add_u32 s30, s54, 0x1cfc0e00
	s_addc_u32 s31, s55, 0
	s_add_u32 s34, s54, 0x1cfc0f00
	s_addc_u32 s35, s55, 0
	s_add_u32 s36, s54, 0x1cfc1000
	v_and_b32_e32 v0, 0x1fe0, v180
	v_lshlrev_b32_e32 v1, 3, v1
	s_addc_u32 s37, s55, 0
	v_and_or_b32 v0, v1, 24, v0
	v_bitop3_b32 v1, v216, v181, 1 bitop3:0x6c
	s_add_u32 s38, s54, 0x1cfc1100
	v_lshlrev_b32_e32 v179, 1, v0
	v_and_b32_e32 v0, 0xe7c0, v219
	v_and_b32_e32 v2, 0x17c0, v219
	v_lshlrev_b32_e32 v1, 4, v1
	s_addc_u32 s39, s55, 0
	v_or_b32_e32 v200, v0, v1
	v_or_b32_e32 v201, v2, v1
	v_lshlrev_b32_e32 v1, 4, v218
	s_add_u32 s40, s54, 0x1cfc1200
	v_or_b32_e32 v202, v0, v1
	v_and_b32_e32 v0, 0x380, v176
	s_addc_u32 s41, s55, 0
	v_lshl_or_b32 v0, v222, 2, v0
	s_add_u32 s42, s54, 0x1cfc1300
	v_or_b32_e32 v203, v2, v1
	v_mul_u32_u24_e32 v0, 0xb00, v0
	v_and_b32_e32 v1, 32, v223
	v_mov_b32_e32 v183, 0
	s_addc_u32 s43, s55, 0
	v_or3_b32 v182, v0, v1, v217
	s_add_u32 s44, s54, 0x1cfc3400
	v_or_b32_e32 v0, v215, v214
	s_movk_i32 s6, 0x3ff
	v_lshlrev_b32_e32 v2, 11, v220
	v_mov_b32_e32 v3, v183
	s_addc_u32 s45, s55, 0
	v_and_or_b32 v4, v0, s6, v176
	v_and_b32_e32 v0, 48, v178
	v_mov_b32_e32 v1, v183
	v_lshl_add_u64 v[184:185], s[54:55], 0, v[2:3]
	s_add_u32 s46, s54, 0x1cfc3500
	v_lshl_add_u64 v[186:187], v[184:185], 0, v[0:1]
	s_mov_b64 s[6:7], 0x1b00000
	s_mul_i32 s88, s88, 24
	s_addc_u32 s47, s55, 0
	v_lshl_add_u64 v[188:189], v[186:187], 0, s[6:7]
	v_lshlrev_b32_e32 v190, 4, v177
	v_mov_b32_e32 v191, v183
	s_mov_b32 s91, 0x20000
	v_mov_b32_e32 v204, 0x10008
	v_mov_b32_e32 v205, 0x10000
	v_mov_b32_e32 v206, 0x10004
	v_mov_b32_e32 v207, 1
	s_mov_b32 s92, 0
	s_mov_b32 s49, 0
	v_cmp_eq_u32_e64 s[6:7], 0, v4
	s_mov_b64 s[50:51], 0x80
	s_branch .LBB0_172
